# GLA scan state wave: the 16 decay-table LDS reads of a step issued up front with counted lgkmcnt waits instead of 16 serialized round trips
# speedup vs baseline: 1.0043x; 1.0026x over previous
; #define LAS __attribute__((address_space(3)))
; #define MFMA32(a, b, c) __builtin_amdgcn_mfma_f32_32x32x16_bf16((a), (b), (c), 0, 0, 0)
; template <int PASS>
; __device__ __forceinline__ void gla_scan3(LAS unsigned char* lds, bf16_t* P  , const bf16_t* QM, const bf16_t* KM, const bf16_t* AQ, const float* EL, bf16_t* OB  , float* SEND, float* DSUM) {
;     ...
; #pragma unroll
;                 for (int kt = 0; kt < 4; ++kt)
; #pragma unroll
;                     for (int g4 = 0; g4 < 4; ++g4) { const f32x4 ev = *(const LAS f32x4*)(el + 32 * kt + 8 * g4 + 4 * h);
; #pragma unroll
;                         for (int e = 0; e < 4; ++e) S[kt][4 * g4 + e] *= ev[e]; }
;                 bf16x8 Vf[4];
; #pragma unroll
;                 for (int ks = 0; ks < 4; ++ks) Vf[ks] = frag_tr(Vb, 136, 32 * w, ks, lane);
;                 if (PASS == 1) {
;                     f32x16 O[2];
; #pragma unroll
;                     for (int mt = 0; mt < 2; ++mt) {
; #pragma unroll
;                         for (int x = 0; x < 16; ++x) O[mt][x] = 0.f;
; #pragma unroll
;                         for (int ks = 0; ks < 4; ++ks) if (ks < 2 * mt + 2) O[mt] = MFMA32(frag_perm(Ab, 72, 32 * mt + r, ks, h), Vf[ks], O[mt]);
;                     }
; #pragma unroll
;                     for (int ks = 0; ks < 8; ++ks) {
;                         const bf16x8 sp = pack_step(S[ks >> 1], ks & 1);
; #pragma unroll
;                         for (int mt = 0; mt < 2; ++mt) O[mt] = MFMA32(frag_perm(Qm, 136, 32 * mt + r, ks, h), sp, O[mt]);
.LBB0_272:
	s_bitcmp1_b32 s63, 0
	s_cselect_b32 s0, 0xf200, 0
	v_bfe_u32 v115, v0, 5, 1
	s_add_i32 s67, s0, 0
	v_lshl_add_u32 v74, v115, 4, s67
	ds_read_b128 v[66:69], v74 offset:61440
	ds_read_b128 v[70:73], v74 offset:61472
	ds_read_b128 v[134:137], v74 offset:61504
	ds_read_b128 v[138:141], v74 offset:61536
	ds_read_b128 v[142:145], v74 offset:61568
	ds_read_b128 v[146:149], v74 offset:61600
	ds_read_b128 v[150:153], v74 offset:61632
	ds_read_b128 v[154:157], v74 offset:61664
	ds_read_b128 v[158:161], v74 offset:61696
	ds_read_b128 v[162:165], v74 offset:61728
	ds_read_b128 v[166:169], v74 offset:61760
	ds_read_b128 v[170:173], v74 offset:61792
	ds_read_b128 v[174:177], v74 offset:61824
	s_add_i32 s0, s67, s19
	v_and_b32_e32 v116, 31, v0
	v_lshlrev_b32_e32 v119, 3, v115
	s_waitcnt lgkmcnt(12)
	v_pk_mul_f32 v[50:51], v[50:51], v[66:67]
	v_pk_mul_f32 v[52:53], v[52:53], v[68:69]
	ds_read_b128 v[66:69], v74 offset:61856
	s_waitcnt lgkmcnt(12)
	v_pk_mul_f32 v[54:55], v[54:55], v[70:71]
	v_pk_mul_f32 v[56:57], v[56:57], v[72:73]
	ds_read_b128 v[70:73], v74 offset:61888
	v_mul_u32_u24_e32 v115, 0x440, v115
	v_cvt_pk_bf16_f32 v125, v56, v57
	s_waitcnt lgkmcnt(12)
	v_pk_mul_f32 v[58:59], v[58:59], v[134:135]
	v_pk_mul_f32 v[60:61], v[60:61], v[136:137]
	ds_read_b128 v[134:137], v74 offset:61920
	s_lshl_b32 s68, s48, 6
	s_mov_b64 s[48:49], -1
	s_andn2_b64 vcc, exec, s[46:47]
	s_waitcnt lgkmcnt(12)
	v_pk_mul_f32 v[62:63], v[62:63], v[138:139]
	v_pk_mul_f32 v[64:65], v[64:65], v[140:141]
	s_waitcnt lgkmcnt(11)
	v_pk_mul_f32 v[34:35], v[34:35], v[142:143]
	v_pk_mul_f32 v[36:37], v[36:37], v[144:145]
	s_waitcnt lgkmcnt(10)
	v_pk_mul_f32 v[38:39], v[38:39], v[146:147]
	v_pk_mul_f32 v[40:41], v[40:41], v[148:149]
	s_waitcnt lgkmcnt(9)
	v_pk_mul_f32 v[42:43], v[42:43], v[150:151]
	v_pk_mul_f32 v[44:45], v[44:45], v[152:153]
	s_waitcnt lgkmcnt(8)
	v_pk_mul_f32 v[46:47], v[46:47], v[154:155]
	v_pk_mul_f32 v[48:49], v[48:49], v[156:157]
	s_waitcnt lgkmcnt(7)
	v_pk_mul_f32 v[18:19], v[18:19], v[158:159]
	v_pk_mul_f32 v[20:21], v[20:21], v[160:161]
	s_waitcnt lgkmcnt(6)
	v_pk_mul_f32 v[22:23], v[22:23], v[162:163]
	v_pk_mul_f32 v[24:25], v[24:25], v[164:165]
	s_waitcnt lgkmcnt(5)
	v_pk_mul_f32 v[26:27], v[26:27], v[166:167]
	v_pk_mul_f32 v[28:29], v[28:29], v[168:169]
	s_waitcnt lgkmcnt(4)
	v_pk_mul_f32 v[30:31], v[30:31], v[170:171]
	v_pk_mul_f32 v[32:33], v[32:33], v[172:173]
	s_waitcnt lgkmcnt(3)
	v_pk_mul_f32 v[2:3], v[2:3], v[174:175]
	v_pk_mul_f32 v[4:5], v[4:5], v[176:177]
	s_waitcnt lgkmcnt(2)
	v_pk_mul_f32 v[6:7], v[6:7], v[66:67]
	v_pk_mul_f32 v[8:9], v[8:9], v[68:69]
	s_waitcnt lgkmcnt(1)
	v_pk_mul_f32 v[10:11], v[10:11], v[70:71]
	v_pk_mul_f32 v[12:13], v[12:13], v[72:73]
	s_waitcnt lgkmcnt(0)
	v_pk_mul_f32 v[14:15], v[14:15], v[134:135]
	v_bfe_u32 v66, v0, 2, 2
	v_lshrrev_b32_e32 v67, 3, v0
	v_and_or_b32 v66, v67, 4, v66
	v_lshlrev_b32_e32 v67, 1, v0
	v_and_b32_e32 v117, 32, v67
	v_mul_u32_u24_e32 v118, 0x110, v66
	v_lshlrev_b32_e32 v66, 3, v0
	v_add_u32_e32 v67, s0, v117
	v_and_b32_e32 v114, 24, v66
	v_add3_u32 v66, v67, v114, v118
	ds_read_b64_tr_b16 v[110:111], v66 offset:34816
	ds_read_b64_tr_b16 v[112:113], v66 offset:36992
	ds_read_b64_tr_b16 v[106:107], v66 offset:39168
	ds_read_b64_tr_b16 v[108:109], v66 offset:41344
	ds_read_b64_tr_b16 v[102:103], v66 offset:43520
	ds_read_b64_tr_b16 v[104:105], v66 offset:45696
	ds_read_b64_tr_b16 v[98:99], v66 offset:47872
	ds_read_b64_tr_b16 v[100:101], v66 offset:50048
	v_mul_u32_u24_e32 v66, 0x90, v116
	v_add3_u32 v74, s67, v66, v119
	v_add_u32_e32 v70, 0xc800, v74
	v_pk_mul_f32 v[16:17], v[16:17], v[136:137]
	ds_read2_b64 v[66:69], v70 offset0:128 offset1:130
	ds_read2_b64 v[70:73], v70 offset0:132 offset1:134
	v_add_u32_e32 v124, 0xd800, v74
	s_waitcnt lgkmcnt(1)
	v_mfma_f32_32x32x16_bf16 v[82:97], v[66:69], v[110:113], 0
	ds_read2_b64 v[66:69], v124 offset0:192 offset1:194
	ds_read2_b64 v[120:123], v124 offset0:196 offset1:198
	s_waitcnt lgkmcnt(2)
	v_mfma_f32_32x32x16_bf16 v[82:97], v[70:73], v[106:109], v[82:97]
	s_waitcnt lgkmcnt(1)
	v_mfma_f32_32x32x16_bf16 v[66:81], v[66:69], v[110:113], 0
	s_waitcnt lgkmcnt(0)
	v_mfma_f32_32x32x16_bf16 v[66:81], v[120:123], v[106:109], v[66:81]
	ds_read2_b64 v[120:123], v124 offset0:200 offset1:202
	s_waitcnt lgkmcnt(0)
	v_mfma_f32_32x32x16_bf16 v[66:81], v[120:123], v[102:105], v[66:81]
	ds_read2_b64 v[120:123], v124 offset0:204 offset1:206
	v_cvt_pk_bf16_f32 v124, v54, v55
	s_waitcnt lgkmcnt(0)
	v_mfma_f32_32x32x16_bf16 v[66:81], v[120:123], v[98:101], v[66:81]
	v_mul_u32_u24_e32 v120, 0x110, v116
	v_add3_u32 v119, s67, v120, v119
	ds_read2_b64 v[126:129], v119 offset1:2
	ds_read2_b64 v[130:133], v119 offset0:4 offset1:6
	v_cvt_pk_bf16_f32 v122, v50, v51
	v_cvt_pk_bf16_f32 v123, v52, v53
	v_add_u32_e32 v120, 0x2000, v119
	v_lshlrev_b32_e32 v116, 1, v116
	s_waitcnt lgkmcnt(1)
	v_mfma_f32_32x32x16_bf16 v[82:97], v[126:129], v[122:125], v[82:97]
	ds_read2_b64 v[126:129], v120 offset0:64 offset1:66
	v_add3_u32 v115, s0, v116, v115
	s_waitcnt lgkmcnt(0)
	v_mfma_f32_32x32x16_bf16 v[66:81], v[126:129], v[122:125], v[66:81]
	ds_read2_b64 v[126:129], v120 offset0:68 offset1:70
	v_cvt_pk_bf16_f32 v122, v58, v59
	v_cvt_pk_bf16_f32 v123, v60, v61
	v_cvt_pk_bf16_f32 v124, v62, v63
	v_cvt_pk_bf16_f32 v125, v64, v65
	s_waitcnt lgkmcnt(0)
	s_nop 0
	v_mfma_f32_32x32x16_bf16 v[66:81], v[126:129], v[122:125], v[66:81]
	ds_read2_b64 v[126:129], v119 offset0:8 offset1:10
	v_mfma_f32_32x32x16_bf16 v[82:97], v[130:133], v[122:125], v[82:97]
	v_cvt_pk_bf16_f32 v122, v34, v35
	v_cvt_pk_bf16_f32 v123, v36, v37
	v_cvt_pk_bf16_f32 v124, v38, v39
	v_cvt_pk_bf16_f32 v125, v40, v41
	s_waitcnt lgkmcnt(0)
; __device__ __forceinline__ int crow(int r, int hi) { return (r & 3) + 8 * (r >> 2) + 4 * hi; }
; __device__ __forceinline__ bf16_t f2bf(float f) { return (bf16_t)(cvtpk_s(f, 0.f) & 0xffffu); }
; __device__ __forceinline__ int crow(int x, int h) { return (x & 3) + 8 * (x >> 2) + 4 * h; }
; #define MFMA32(a, b, c) __builtin_amdgcn_mfma_f32_32x32x16_bf16((a), (b), (c), 0, 0, 0)
; template <int PASS>
; __device__ __forceinline__ void gla_scan3(LAS unsigned char* lds, bf16_t* P  , const bf16_t* QM, const bf16_t* KM, const bf16_t* AQ, const float* EL, bf16_t* OB  , float* SEND, float* DSUM) {
;     ...
;                     for (int ks = 0; ks < 8; ++ks) {
;                         const bf16x8 sp = pack_step(S[ks >> 1], ks & 1);
; #pragma unroll
;                         for (int mt = 0; mt < 2; ++mt) O[mt] = MFMA32(frag_perm(Qm, 136, 32 * mt + r, ks, h), sp, O[mt]);
;                     }
; #pragma unroll
;                     for (int mt = 0; mt < 2; ++mt)
; #pragma unroll
;                         for (int x = 0; x < 16; ++x) Vb[(32 * mt + crow(x, h)) * 136 + 32 * w + r] = f2bf(O[mt][x]);
	s_nop 0
	v_mfma_f32_32x32x16_bf16 v[82:97], v[126:129], v[122:125], v[82:97]
	ds_read2_b64 v[126:129], v120 offset0:72 offset1:74
	s_waitcnt lgkmcnt(0)
	v_mfma_f32_32x32x16_bf16 v[66:81], v[126:129], v[122:125], v[66:81]
	ds_read2_b64 v[126:129], v119 offset0:12 offset1:14
	v_cvt_pk_bf16_f32 v122, v42, v43
	v_cvt_pk_bf16_f32 v123, v44, v45
	v_cvt_pk_bf16_f32 v124, v46, v47
	v_cvt_pk_bf16_f32 v125, v48, v49
	s_waitcnt lgkmcnt(0)
	s_nop 0
	v_mfma_f32_32x32x16_bf16 v[82:97], v[126:129], v[122:125], v[82:97]
	ds_read2_b64 v[126:129], v120 offset0:76 offset1:78
	s_waitcnt lgkmcnt(0)
	v_mfma_f32_32x32x16_bf16 v[66:81], v[126:129], v[122:125], v[66:81]
	ds_read2_b64 v[126:129], v119 offset0:16 offset1:18
	v_cvt_pk_bf16_f32 v122, v18, v19
	v_cvt_pk_bf16_f32 v123, v20, v21
	v_cvt_pk_bf16_f32 v124, v22, v23
	v_cvt_pk_bf16_f32 v125, v24, v25
	s_waitcnt lgkmcnt(0)
	s_nop 0
	v_mfma_f32_32x32x16_bf16 v[82:97], v[126:129], v[122:125], v[82:97]
	ds_read2_b64 v[126:129], v120 offset0:80 offset1:82
	s_waitcnt lgkmcnt(0)
	v_mfma_f32_32x32x16_bf16 v[66:81], v[126:129], v[122:125], v[66:81]
	ds_read2_b64 v[126:129], v119 offset0:20 offset1:22
	v_cvt_pk_bf16_f32 v122, v26, v27
	v_cvt_pk_bf16_f32 v123, v28, v29
	v_cvt_pk_bf16_f32 v124, v30, v31
	v_cvt_pk_bf16_f32 v125, v32, v33
	s_waitcnt lgkmcnt(0)
	s_nop 0
	v_mfma_f32_32x32x16_bf16 v[82:97], v[126:129], v[122:125], v[82:97]
	ds_read2_b64 v[126:129], v120 offset0:84 offset1:86
	s_waitcnt lgkmcnt(0)
	v_mfma_f32_32x32x16_bf16 v[66:81], v[126:129], v[122:125], v[66:81]
	ds_read2_b64 v[126:129], v119 offset0:24 offset1:26
	v_cvt_pk_bf16_f32 v122, v2, v3
	v_cvt_pk_bf16_f32 v123, v4, v5
	v_cvt_pk_bf16_f32 v124, v6, v7
	v_cvt_pk_bf16_f32 v125, v8, v9
	s_waitcnt lgkmcnt(0)
	s_nop 0
	v_mfma_f32_32x32x16_bf16 v[82:97], v[126:129], v[122:125], v[82:97]
	ds_read2_b64 v[126:129], v120 offset0:88 offset1:90
	s_waitcnt lgkmcnt(0)
	v_mfma_f32_32x32x16_bf16 v[66:81], v[126:129], v[122:125], v[66:81]
	ds_read2_b64 v[126:129], v119 offset0:28 offset1:30
	v_cvt_pk_bf16_f32 v122, v10, v11
	v_cvt_pk_bf16_f32 v123, v12, v13
	v_cvt_pk_bf16_f32 v124, v14, v15
	v_cvt_pk_bf16_f32 v125, v16, v17
	s_waitcnt lgkmcnt(0)
	s_nop 0
	v_mfma_f32_32x32x16_bf16 v[82:97], v[126:129], v[122:125], v[82:97]
	ds_read2_b64 v[126:129], v120 offset0:92 offset1:94
	s_waitcnt lgkmcnt(0)
	v_mfma_f32_32x32x16_bf16 v[66:81], v[126:129], v[122:125], v[66:81]
	s_nop 8
	v_cvt_pk_bf16_f32 v82, v82, s0
	ds_write_b16 v115, v82 offset:34816
	v_cvt_pk_bf16_f32 v82, v83, s0
	ds_write_b16 v115, v82 offset:35088
	v_cvt_pk_bf16_f32 v82, v84, s0
	ds_write_b16 v115, v82 offset:35360
	v_cvt_pk_bf16_f32 v82, v85, s0
	v_cvt_pk_bf16_f32 v66, v66, s0
	ds_write_b16 v115, v66 offset:43520
	v_cvt_pk_bf16_f32 v66, v67, s0
	ds_write_b16 v115, v66 offset:43792
	v_cvt_pk_bf16_f32 v66, v68, s0
	ds_write_b16 v115, v66 offset:44064
	v_cvt_pk_bf16_f32 v66, v69, s0
	ds_write_b16 v115, v66 offset:44336
	v_cvt_pk_bf16_f32 v66, v70, s0
	ds_write_b16 v115, v82 offset:35632
	v_cvt_pk_bf16_f32 v82, v86, s0
	ds_write_b16 v115, v66 offset:45696
	v_cvt_pk_bf16_f32 v66, v71, s0
	ds_write_b16 v115, v82 offset:36992
	v_cvt_pk_bf16_f32 v82, v87, s0
	ds_write_b16 v115, v66 offset:45968
	v_cvt_pk_bf16_f32 v66, v72, s0
	ds_write_b16 v115, v82 offset:37264
	v_cvt_pk_bf16_f32 v82, v88, s0
	ds_write_b16 v115, v66 offset:46240
	v_cvt_pk_bf16_f32 v66, v73, s0
	ds_write_b16 v115, v82 offset:37536
	v_cvt_pk_bf16_f32 v82, v89, s0
	ds_write_b16 v115, v66 offset:46512
	v_cvt_pk_bf16_f32 v66, v74, s0
	ds_write_b16 v115, v82 offset:37808
	v_cvt_pk_bf16_f32 v82, v90, s0
	ds_write_b16 v115, v66 offset:47872
	v_cvt_pk_bf16_f32 v66, v75, s0
	ds_write_b16 v115, v82 offset:39168
	v_cvt_pk_bf16_f32 v82, v91, s0
	ds_write_b16 v115, v66 offset:48144
	v_cvt_pk_bf16_f32 v66, v76, s0
	ds_write_b16 v115, v82 offset:39440
	v_cvt_pk_bf16_f32 v82, v92, s0
	ds_write_b16 v115, v66 offset:48416
	v_cvt_pk_bf16_f32 v66, v77, s0
	ds_write_b16 v115, v82 offset:39712
	v_cvt_pk_bf16_f32 v82, v93, s0
	ds_write_b16 v115, v66 offset:48688
	v_cvt_pk_bf16_f32 v66, v78, s0
	ds_write_b16 v115, v82 offset:39984
	v_cvt_pk_bf16_f32 v82, v94, s0
	ds_write_b16 v115, v66 offset:50048
	v_cvt_pk_bf16_f32 v66, v79, s0
	ds_write_b16 v115, v82 offset:41344
	v_cvt_pk_bf16_f32 v82, v95, s0
	ds_write_b16 v115, v66 offset:50320
	v_cvt_pk_bf16_f32 v66, v80, s0
	ds_write_b16 v115, v82 offset:41616
	v_cvt_pk_bf16_f32 v82, v96, s0
	ds_write_b16 v115, v66 offset:50592
	v_cvt_pk_bf16_f32 v66, v81, s0
	ds_write_b16 v115, v82 offset:41888
	v_cvt_pk_bf16_f32 v82, v97, s0
	ds_write_b16 v115, v66 offset:50864
	v_add_u32_e32 v66, s67, v117
	ds_write_b16 v115, v82 offset:42160
	v_add3_u32 v70, v66, v114, v118
	ds_read_b64_tr_b16 v[66:67], v70 offset:17408
	ds_read_b64_tr_b16 v[68:69], v70 offset:19584
	s_waitcnt lgkmcnt(0)
; #define MFMA32(a, b, c) __builtin_amdgcn_mfma_f32_32x32x16_bf16((a), (b), (c), 0, 0, 0)
; template <int PASS>
; __device__ __forceinline__ void gla_scan3(LAS unsigned char* lds, bf16_t* P  , const bf16_t* QM, const bf16_t* KM, const bf16_t* AQ, const float* EL, bf16_t* OB  , float* SEND, float* DSUM) {
;     ...
; #pragma unroll
;                 for (int ks = 0; ks < 4; ++ks) {
; #pragma unroll
;                     for (int kt = 0; kt < 4; ++kt) S[kt] = MFMA32(frag_tr(Km, 136, 32 * kt, ks, lane), Vf[ks], S[kt]);
;                 }
;                 if (PASS == 1) {
;                     asm volatile("s_waitcnt lgkmcnt(0)" ::: "memory");
;                     const int rr_ = lane >> 2, c8_ = 8 * (lane & 3);
; #pragma unroll
;                     for (int v = 0; v < 4; ++v) { const int ip_ = rr_ + 16 * v, i_ = dir ? 63 - ip_ : ip_; const int oc_ = head * 256 + hf * 128 + 32 * w + c8_;
;                         bf16_t* dst_ = dir ? P + (size_t)(rb * 64 + i_) * 3072 + oc_ : OB + (size_t)(rb * 64 + i_) * 1024 + oc_;
	v_mfma_f32_32x32x16_bf16 v[50:65], v[66:69], v[110:113], v[50:65]
	ds_read_b64_tr_b16 v[66:67], v70 offset:17472
	ds_read_b64_tr_b16 v[68:69], v70 offset:19648
	v_bfe_u32 v74, v0, 2, 4
	v_or_b32_e32 v0, s66, v114
	v_lshlrev_b32_e32 v0, 1, v0
	s_waitcnt lgkmcnt(0)
	v_mfma_f32_32x32x16_bf16 v[34:49], v[66:69], v[110:113], v[34:49]
	ds_read_b64_tr_b16 v[66:67], v70 offset:17536
	ds_read_b64_tr_b16 v[68:69], v70 offset:19712
	s_waitcnt lgkmcnt(0)
	v_mfma_f32_32x32x16_bf16 v[18:33], v[66:69], v[110:113], v[18:33]
	ds_read_b64_tr_b16 v[66:67], v70 offset:17600
	ds_read_b64_tr_b16 v[68:69], v70 offset:19776
	s_waitcnt lgkmcnt(0)
	v_mfma_f32_32x32x16_bf16 v[2:17], v[66:69], v[110:113], v[2:17]
	ds_read_b64_tr_b16 v[66:67], v70 offset:21760
	ds_read_b64_tr_b16 v[68:69], v70 offset:23936
	s_waitcnt lgkmcnt(0)
	v_mfma_f32_32x32x16_bf16 v[50:65], v[66:69], v[106:109], v[50:65]
	ds_read_b64_tr_b16 v[66:67], v70 offset:21824
	ds_read_b64_tr_b16 v[68:69], v70 offset:24000
	s_waitcnt lgkmcnt(0)
	v_mfma_f32_32x32x16_bf16 v[34:49], v[66:69], v[106:109], v[34:49]
	ds_read_b64_tr_b16 v[66:67], v70 offset:21888
	ds_read_b64_tr_b16 v[68:69], v70 offset:24064
	s_waitcnt lgkmcnt(0)
	v_mfma_f32_32x32x16_bf16 v[18:33], v[66:69], v[106:109], v[18:33]
	ds_read_b64_tr_b16 v[66:67], v70 offset:21952
	ds_read_b64_tr_b16 v[68:69], v70 offset:24128
	s_waitcnt lgkmcnt(0)
	v_mfma_f32_32x32x16_bf16 v[2:17], v[66:69], v[106:109], v[2:17]
	ds_read_b64_tr_b16 v[66:67], v70 offset:26112
	ds_read_b64_tr_b16 v[68:69], v70 offset:28288
	s_waitcnt lgkmcnt(0)
	v_mfma_f32_32x32x16_bf16 v[50:65], v[66:69], v[102:105], v[50:65]
	ds_read_b64_tr_b16 v[66:67], v70 offset:26176
	ds_read_b64_tr_b16 v[68:69], v70 offset:28352
	s_waitcnt lgkmcnt(0)
	v_mfma_f32_32x32x16_bf16 v[34:49], v[66:69], v[102:105], v[34:49]
	ds_read_b64_tr_b16 v[66:67], v70 offset:26240
	ds_read_b64_tr_b16 v[68:69], v70 offset:28416
	s_waitcnt lgkmcnt(0)
	v_mfma_f32_32x32x16_bf16 v[18:33], v[66:69], v[102:105], v[18:33]
	ds_read_b64_tr_b16 v[66:67], v70 offset:26304
	ds_read_b64_tr_b16 v[68:69], v70 offset:28480
	s_waitcnt lgkmcnt(0)
	v_mfma_f32_32x32x16_bf16 v[2:17], v[66:69], v[102:105], v[2:17]
	ds_read_b64_tr_b16 v[66:67], v70 offset:30464
	ds_read_b64_tr_b16 v[68:69], v70 offset:32640
	s_waitcnt lgkmcnt(0)
	v_mfma_f32_32x32x16_bf16 v[50:65], v[66:69], v[98:101], v[50:65]
	ds_read_b64_tr_b16 v[66:67], v70 offset:30528
	ds_read_b64_tr_b16 v[68:69], v70 offset:32704
	s_waitcnt lgkmcnt(0)
	v_mfma_f32_32x32x16_bf16 v[34:49], v[66:69], v[98:101], v[34:49]
	ds_read_b64_tr_b16 v[66:67], v70 offset:30592
	ds_read_b64_tr_b16 v[68:69], v70 offset:32768
	s_waitcnt lgkmcnt(0)
	v_mfma_f32_32x32x16_bf16 v[18:33], v[66:69], v[98:101], v[18:33]
	ds_read_b64_tr_b16 v[66:67], v70 offset:30656
	ds_read_b64_tr_b16 v[68:69], v70 offset:32832
	s_waitcnt lgkmcnt(0)
	s_waitcnt lgkmcnt(0)
	v_mfma_f32_32x32x16_bf16 v[2:17], v[66:69], v[98:101], v[2:17]
	v_cndmask_b32_e64 v69, 0, 1, s[46:47]
	v_lshl_add_u64 v[66:67], s[96:97], 0, v[0:1]
	v_or_b32_e32 v68, s68, v74
	v_cmp_ne_u32_e64 s[0:1], 1, v69
	s_cbranch_vccnz .LBB0_274
	v_xor_b32_e32 v69, 63, v68
	v_mad_i64_i32 v[72:73], s[48:49], v69, s79, v[66:67]
	s_mov_b64 s[48:49], 0
